# hyena lag loop: counted lgkmcnt waits (window lgkmcnt(8), per-MFMA lgkmcnt(12)) so prefetch reads stay in flight
# baseline (speedup 1.0000x reference)
; DI void hyena_conv(const bf16_t* sK, const bf16_t* sZ, f32x16 (&acc)[4], int q, int lane) {
;   const int r = lane & 31, h = lane >> 5;
;   const int phi = (7 - r) & 7;
;   const bool pb0 = (phi >> 1) & 1, pb1 = (phi >> 2) & 1;
;   const unsigned psh = (phi & 1) * 16;
; #pragma unroll
;   for (int bb = 0; bb < 4; ++bb)
; #pragma unroll
;     for (int i = 0; i < 16; ++i) acc[bb][i] = 0.f;
;   int dlo = 32 * q - 127, dhi = 32 * q + 31;
;   asm volatile("" : "+s"(dlo), "+s"(dhi));
;   for (int d = dlo; d < dhi; d += 2) {
;     HY_BODY(d)
;     HY_BODY(d + 1)
;   }
.LBB0_579:
	s_waitcnt lgkmcnt(8)
	v_alignbit_b32 v72, v243, v242, v83
	v_alignbit_b32 v73, v244, v243, v83
	v_alignbit_b32 v74, v245, v244, v83
	v_alignbit_b32 v75, v246, v245, v83
	v_alignbit_b32 v76, v248, v247, v83
	v_alignbit_b32 v77, v249, v248, v83
	v_alignbit_b32 v78, v250, v249, v83
	v_alignbit_b32 v79, v251, v250, v83
	ds_read2_b32 v[242:243], v240 offset0:0 offset1:1
	ds_read2_b32 v[244:245], v240 offset0:2 offset1:3
	ds_read2_b32 v[246:247], v240 offset0:4 offset1:8
	ds_read2_b32 v[248:249], v240 offset0:9 offset1:10
	ds_read2_b32 v[250:251], v240 offset0:11 offset1:12
	v_add_u32_e32 v99, v95, v87
	s_waitcnt lgkmcnt(12)
	v_mfma_f32_32x32x16_bf16 v[48:63], v[72:75], v[144:147], v[48:63]
	ds_read_b128 v[176:179], v99
	s_waitcnt lgkmcnt(12)
	v_mfma_f32_32x32x16_bf16 v[48:63], v[76:79], v[148:151], v[48:63]
	ds_read_b128 v[180:183], v99 offset:32
	s_add_i32 s36, s36, 2
	v_add_u32_e32 v91, 0xffffff60, v91
	v_add_u32_e32 v93, 0xffffff80, v93
	s_cmp_lt_i32 s36, s0
	s_waitcnt lgkmcnt(12)
	v_mfma_f32_32x32x16_bf16 v[32:47], v[72:75], v[152:155], v[32:47]
	ds_read_b128 v[184:187], v99 offset:15360
	s_waitcnt lgkmcnt(12)
	v_mfma_f32_32x32x16_bf16 v[32:47], v[76:79], v[156:159], v[32:47]
	ds_read_b128 v[212:215], v99 offset:15392
	s_waitcnt lgkmcnt(12)
	v_mfma_f32_32x32x16_bf16 v[16:31], v[72:75], v[160:163], v[16:31]
	ds_read_b128 v[216:219], v99 offset:30720
	s_waitcnt lgkmcnt(12)
	v_mfma_f32_32x32x16_bf16 v[16:31], v[76:79], v[164:167], v[16:31]
	ds_read_b128 v[220:223], v99 offset:30752
	s_waitcnt lgkmcnt(12)
	v_mfma_f32_32x32x16_bf16 v[0:15], v[72:75], v[168:171], v[0:15]
	ds_read_b128 v[224:227], v99 offset:46080
	s_waitcnt lgkmcnt(12)
	v_mfma_f32_32x32x16_bf16 v[0:15], v[76:79], v[172:175], v[0:15]
	ds_read_b128 v[228:231], v99 offset:46112
	s_waitcnt lgkmcnt(8)
	v_alignbit_b32 v72, v243, v242, v83
	v_alignbit_b32 v73, v244, v243, v83
	v_alignbit_b32 v74, v245, v244, v83
	v_alignbit_b32 v75, v246, v245, v83
	v_alignbit_b32 v76, v248, v247, v83
	v_alignbit_b32 v77, v249, v248, v83
	v_alignbit_b32 v78, v250, v249, v83
	v_alignbit_b32 v79, v251, v250, v83
	v_add_u32_e32 v240, v93, v241
	ds_read2_b32 v[242:243], v240 offset0:16 offset1:17
	ds_read2_b32 v[244:245], v240 offset0:18 offset1:19
	ds_read2_b32 v[246:247], v240 offset0:20 offset1:24
	ds_read2_b32 v[248:249], v240 offset0:25 offset1:26
	ds_read2_b32 v[250:251], v240 offset0:27 offset1:28
	v_add_u32_e32 v101, v91, v87
	s_waitcnt lgkmcnt(12)
	v_mfma_f32_32x32x16_bf16 v[48:63], v[72:75], v[176:179], v[48:63]
	ds_read_b128 v[144:147], v101
	s_waitcnt lgkmcnt(12)
	v_mfma_f32_32x32x16_bf16 v[48:63], v[76:79], v[180:183], v[48:63]
	ds_read_b128 v[148:151], v101 offset:32
	v_add_u32_e32 v95, 0xffffff60, v95
	s_waitcnt lgkmcnt(12)
	v_mfma_f32_32x32x16_bf16 v[32:47], v[72:75], v[184:187], v[32:47]
	ds_read_b128 v[152:155], v101 offset:15360
	s_waitcnt lgkmcnt(12)
	v_mfma_f32_32x32x16_bf16 v[32:47], v[76:79], v[212:215], v[32:47]
	ds_read_b128 v[156:159], v101 offset:15392
	s_waitcnt lgkmcnt(12)
	v_mfma_f32_32x32x16_bf16 v[16:31], v[72:75], v[216:219], v[16:31]
	ds_read_b128 v[160:163], v101 offset:30720
	s_waitcnt lgkmcnt(12)
	v_mfma_f32_32x32x16_bf16 v[16:31], v[76:79], v[220:223], v[16:31]
	ds_read_b128 v[164:167], v101 offset:30752
	s_waitcnt lgkmcnt(12)
	v_mfma_f32_32x32x16_bf16 v[0:15], v[72:75], v[224:227], v[0:15]
	ds_read_b128 v[168:171], v101 offset:46080
	s_waitcnt lgkmcnt(12)
	v_mfma_f32_32x32x16_bf16 v[0:15], v[76:79], v[228:231], v[0:15]
	ds_read_b128 v[172:175], v101 offset:46112
	s_cbranch_scc1 .LBB0_579

; DI void hyena_conv(const bf16_t* sK, const bf16_t* sZ, f32x16 (&acc)[4], int q, int lane) {
;   const int r = lane & 31, h = lane >> 5;
;   const int phi = (7 - r) & 7;
;   const bool pb0 = (phi >> 1) & 1, pb1 = (phi >> 2) & 1;
;   const unsigned psh = (phi & 1) * 16;
; #pragma unroll
;   for (int bb = 0; bb < 4; ++bb)
; #pragma unroll
;     for (int i = 0; i < 16; ++i) acc[bb][i] = 0.f;
;   int dlo = 32 * q - 127, dhi = 32 * q + 31;
;   asm volatile("" : "+s"(dlo), "+s"(dhi));
;   for (int d = dlo; d < dhi; d += 2) {
;     HY_BODY(d)
;     HY_BODY(d + 1)
;   }
.LBB0_585:
	s_waitcnt lgkmcnt(8)
	v_alignbit_b32 v68, v243, v242, v83
	v_alignbit_b32 v69, v244, v243, v83
	v_alignbit_b32 v70, v245, v244, v83
	v_alignbit_b32 v71, v246, v245, v83
	v_alignbit_b32 v72, v248, v247, v83
	v_alignbit_b32 v73, v249, v248, v83
	v_alignbit_b32 v74, v250, v249, v83
	v_alignbit_b32 v75, v251, v250, v83
	ds_read2_b32 v[242:243], v240 offset0:0 offset1:1
	ds_read2_b32 v[244:245], v240 offset0:2 offset1:3
	ds_read2_b32 v[246:247], v240 offset0:4 offset1:8
	ds_read2_b32 v[248:249], v240 offset0:9 offset1:10
	ds_read2_b32 v[250:251], v240 offset0:11 offset1:12
	v_add_u32_e32 v94, v93, v87
	s_waitcnt lgkmcnt(12)
	v_mfma_f32_32x32x16_bf16 v[48:63], v[68:71], v[144:147], v[48:63]
	ds_read_b128 v[176:179], v94
	s_waitcnt lgkmcnt(12)
	v_mfma_f32_32x32x16_bf16 v[48:63], v[72:75], v[148:151], v[48:63]
	ds_read_b128 v[180:183], v94 offset:32
	s_add_i32 s28, s28, 2
	v_add_u32_e32 v90, 0xffffff60, v90
	v_add_u32_e32 v92, 0xffffff80, v92
	s_cmp_lt_i32 s28, s11
	s_waitcnt lgkmcnt(12)
	v_mfma_f32_32x32x16_bf16 v[32:47], v[68:71], v[152:155], v[32:47]
	ds_read_b128 v[184:187], v94 offset:15360
	s_waitcnt lgkmcnt(12)
	v_mfma_f32_32x32x16_bf16 v[32:47], v[72:75], v[156:159], v[32:47]
	ds_read_b128 v[212:215], v94 offset:15392
	s_waitcnt lgkmcnt(12)
	v_mfma_f32_32x32x16_bf16 v[16:31], v[68:71], v[160:163], v[16:31]
	ds_read_b128 v[216:219], v94 offset:30720
	s_waitcnt lgkmcnt(12)
	v_mfma_f32_32x32x16_bf16 v[16:31], v[72:75], v[164:167], v[16:31]
	ds_read_b128 v[220:223], v94 offset:30752
	s_waitcnt lgkmcnt(12)
	v_mfma_f32_32x32x16_bf16 v[0:15], v[68:71], v[168:171], v[0:15]
	ds_read_b128 v[224:227], v94 offset:46080
	s_waitcnt lgkmcnt(12)
	v_mfma_f32_32x32x16_bf16 v[0:15], v[72:75], v[172:175], v[0:15]
	ds_read_b128 v[228:231], v94 offset:46112
	s_waitcnt lgkmcnt(8)
	v_alignbit_b32 v68, v243, v242, v83
	v_alignbit_b32 v69, v244, v243, v83
	v_alignbit_b32 v70, v245, v244, v83
	v_alignbit_b32 v71, v246, v245, v83
	v_alignbit_b32 v72, v248, v247, v83
	v_alignbit_b32 v73, v249, v248, v83
	v_alignbit_b32 v74, v250, v249, v83
	v_alignbit_b32 v75, v251, v250, v83
	v_add_u32_e32 v240, v92, v241
	ds_read2_b32 v[242:243], v240 offset0:16 offset1:17
	ds_read2_b32 v[244:245], v240 offset0:18 offset1:19
	ds_read2_b32 v[246:247], v240 offset0:20 offset1:24
	ds_read2_b32 v[248:249], v240 offset0:25 offset1:26
	ds_read2_b32 v[250:251], v240 offset0:27 offset1:28
	v_add_u32_e32 v96, v90, v87
	s_waitcnt lgkmcnt(12)
	v_mfma_f32_32x32x16_bf16 v[48:63], v[68:71], v[176:179], v[48:63]
	ds_read_b128 v[144:147], v96
	s_waitcnt lgkmcnt(12)
	v_mfma_f32_32x32x16_bf16 v[48:63], v[72:75], v[180:183], v[48:63]
	ds_read_b128 v[148:151], v96 offset:32
	v_add_u32_e32 v93, 0xffffff60, v93
	s_waitcnt lgkmcnt(12)
	v_mfma_f32_32x32x16_bf16 v[32:47], v[68:71], v[184:187], v[32:47]
	ds_read_b128 v[152:155], v96 offset:15360
	s_waitcnt lgkmcnt(12)
	v_mfma_f32_32x32x16_bf16 v[32:47], v[72:75], v[212:215], v[32:47]
	ds_read_b128 v[156:159], v96 offset:15392
	s_waitcnt lgkmcnt(12)
	v_mfma_f32_32x32x16_bf16 v[16:31], v[68:71], v[216:219], v[16:31]
	ds_read_b128 v[160:163], v96 offset:30720
	s_waitcnt lgkmcnt(12)
	v_mfma_f32_32x32x16_bf16 v[16:31], v[72:75], v[220:223], v[16:31]
	ds_read_b128 v[164:167], v96 offset:30752
	s_waitcnt lgkmcnt(12)
	v_mfma_f32_32x32x16_bf16 v[0:15], v[68:71], v[224:227], v[0:15]
	ds_read_b128 v[168:171], v96 offset:46080
	s_waitcnt lgkmcnt(12)
	v_mfma_f32_32x32x16_bf16 v[0:15], v[72:75], v[228:231], v[0:15]
	ds_read_b128 v[172:175], v96 offset:46112
	s_cbranch_scc1 .LBB0_585
	s_branch .LBB0_567

; DI unsigned pack2(float lo, float hi) { f32x2_t v = {lo, hi}; bf16x2_t r = __builtin_convertvector(v, bf16x2_t); return __builtin_bit_cast(unsigned, r); }
; DI float xhalf_sum(float x) { auto r = __builtin_amdgcn_permlane32_swap(__float_as_uint(x), __float_as_uint(x), false, false); return __uint_as_float(r[0]) + __uint_as_float(r[1]); }
; template <int DQK>
; DI void attn_item(const bf16_t* __restrict__ Q, const bf16_t* __restrict__ Kp, const bf16_t* __restrict__ Vt, int q0, int nkeys,
;                   bf16_t* __restrict__ mix, int colbase, int b, char* smem) {
;     ...
;   l = xhalf_sum(l);
;   const float inv = 1.0f / l;
;   const int kp = q0 + wave * 32 + r;
;   bf16_t* orow = mix + (size_t)row_of(b, kp) * D + colbase;
; #pragma unroll
;   for (int g = 0; g < 4; ++g) {
;     uint2 w0, w1;
;     w0.x = pack2(o0[4 * g] * inv, o0[4 * g + 1] * inv); w0.y = pack2(o0[4 * g + 2] * inv, o0[4 * g + 3] * inv);
;     w1.x = pack2(o1[4 * g] * inv, o1[4 * g + 1] * inv); w1.y = pack2(o1[4 * g + 2] * inv, o1[4 * g + 3] * inv);
;     *(uint2*)(orow + 8 * g + 4 * h) = w0;
;     *(uint2*)(orow + 32 + 8 * g + 4 * h) = w1;
;   }
; DI void phase_attn(const Params& p, int layer, char* smem) {
;     ...
;   for (int it = blockIdx.x; it < n_lat + n_ctx; it += gridDim.x) {
;     int combo, qb;
;     if (it < n_lat) { int xc = it & 7, j = it >> 3; combo = (j >> 5) * 8 + xc; qb = 2 + (j & 31); }
;     else { int r = it - n_lat; combo = r >> 1; qb = r & 1; }
;     const int type = combo / 48, bh = combo % 48;
;     attn_dispatch(p, type, bh / 6, bh % 6, qb, smem);
.Lat2_done:
	s_setprio 0
	s_waitcnt vmcnt(0)
	s_barrier
	v_lshlrev_b32_e32 v248, 2, v143
	v_add_u32_e32 v248, 0xac00, v248
	ds_read_b32 v136, v248 offset:0
	ds_read_b32 v137, v248 offset:1024
	ds_read_b32 v138, v248 offset:2048
	ds_read_b32 v139, v248 offset:3072
	ds_read_b32 v141, v248 offset:4096
	ds_read_b32 v142, v248 offset:5120
	ds_read_b32 v188, v248 offset:6144
	ds_read_b32 v189, v248 offset:7168
	ds_read_b32 v190, v248 offset:8192
	ds_read_b32 v191, v248 offset:9216
	ds_read_b32 v192, v248 offset:10240
	ds_read_b32 v193, v248 offset:11264
	ds_read_b32 v194, v248 offset:12288
	ds_read_b32 v195, v248 offset:13312
	ds_read_b32 v196, v248 offset:14336
	ds_read_b32 v197, v248 offset:15360
	ds_read_b32 v198, v248 offset:16384
	ds_read_b32 v199, v248 offset:17408
	ds_read_b32 v200, v248 offset:18432
	ds_read_b32 v201, v248 offset:19456
	ds_read_b32 v202, v248 offset:20480
	ds_read_b32 v203, v248 offset:21504
	ds_read_b32 v204, v248 offset:22528
	ds_read_b32 v205, v248 offset:23552
	ds_read_b32 v206, v248 offset:24576
	ds_read_b32 v207, v248 offset:25600
	ds_read_b32 v208, v248 offset:26624
	ds_read_b32 v209, v248 offset:27648
	ds_read_b32 v210, v248 offset:28672
	ds_read_b32 v211, v248 offset:29696
	ds_read_b32 v212, v248 offset:30720
	ds_read_b32 v234, v248 offset:31744
	ds_read_b32 v235, v248 offset:32768
	ds_read_b32 v236, v248 offset:33792
	s_add_u32 s0, s52, 0x600
	v_readlane_b32 s52, v254, 0
	v_readlane_b32 s53, v254, 1
	v_readlane_b32 s54, v254, 2
	v_readlane_b32 s55, v254, 3
	v_readlane_b32 s56, v254, 4
	v_readlane_b32 s57, v254, 5
	v_readlane_b32 s58, v254, 6
	v_readlane_b32 s59, v254, 7
	v_readlane_b32 s60, v254, 8
	v_readlane_b32 s61, v254, 9
	v_readlane_b32 s62, v254, 10
	v_readlane_b32 s63, v254, 11
	v_readlane_b32 s64, v254, 12
	v_readlane_b32 s65, v254, 13
	v_readlane_b32 s66, v254, 14
	v_readlane_b32 s67, v254, 15
	v_readlane_b32 s68, v254, 16
	v_readlane_b32 s69, v254, 17
	v_readlane_b32 s70, v254, 18
	v_readlane_b32 s71, v254, 19
	v_readlane_b32 s72, v254, 20
	v_readlane_b32 s73, v254, 21
	v_readlane_b32 s74, v254, 22
	v_readlane_b32 s75, v254, 23
	v_readlane_b32 s76, v254, 24
	v_readlane_b32 s77, v254, 25
	v_readlane_b32 s78, v254, 26
	v_readlane_b32 s79, v254, 27
	v_readlane_b32 s80, v254, 28
	v_readlane_b32 s81, v254, 29
	v_readlane_b32 s82, v254, 30
	v_readlane_b32 s83, v254, 31
	v_readlane_b32 s84, v254, 32
	v_readlane_b32 s85, v254, 33
	v_readlane_b32 s86, v254, 34
	v_readlane_b32 s87, v254, 35
	v_readlane_b32 s88, v254, 36
	v_readlane_b32 s89, v254, 37
	v_readlane_b32 s90, v254, 38
	v_readlane_b32 s91, v254, 39
	s_waitcnt lgkmcnt(0)
	s_mov_b32 s13, s0
	s_cmp_ge_i32 s13, s12
	s_cbranch_scc0 .LBB0_1453
	s_branch .LBB0_1446
